# P5 conv+gelu epilogue: sigmoid argument of two gates computed with 3 packed f32 ops (g*g, *cK+K, *g) instead of 10 scalar ops
# baseline (speedup 1.0000x reference)
.LBB0_1208:
	v_readlane_b32 s36, v250, 60
	v_readlane_b32 s50, v249, 10
	v_readlane_b32 s51, v249, 11
	s_add_u32 s24, s50, 0x460e000
	s_addc_u32 s25, s51, 0
	s_add_u32 s26, s50, 0x6746000
	v_readlane_b32 s42, v249, 2
	s_addc_u32 s27, s51, 0
	v_readlane_b32 s43, v249, 3
	s_add_u32 s28, s42, 0x5800
	s_addc_u32 s29, s43, 0
	s_add_u32 s30, s42, 0xb000
	s_addc_u32 s31, s43, 0
	s_add_u32 s34, s42, 0x8400
	v_readlane_b32 s38, v250, 62
	v_readlane_b32 s39, v250, 63
	s_addc_u32 s35, s43, 0
	v_readlane_b32 s37, v250, 61
	s_add_u32 s36, s42, 0xdc00
	s_mov_b64 s[38:39], 0x80
	s_addc_u32 s37, s43, 0
	s_and_b32 s88, s7, 3
	s_add_i32 m0, s83, 0x18000
	v_lshl_add_u64 v[6:7], v[6:7], 0, s[38:39]
	s_lshl_b32 s7, s33, 13
	s_lshl_b32 s9, s88, 12
	s_waitcnt vmcnt(2)
	s_barrier
	global_load_lds_dwordx4 v[6:7], off
	v_lshl_add_u64 v[4:5], v[4:5], 0, s[38:39]
	s_add_i32 m0, s83, 0x1a000
	s_add_i32 s89, s83, 0x8000
	s_add_i32 s90, s83, 0xa000
	global_load_lds_dwordx4 v[4:5], off
	v_lshl_add_u64 v[0:1], v[0:1], 0, s[38:39]
	s_mov_b32 m0, s89
	s_add_u32 s12, s2, 0x40080
	global_load_lds_dwordx4 v[0:1], off
	v_lshl_add_u64 v[0:1], v[2:3], 0, s[38:39]
	s_mov_b32 m0, s90
	s_addc_u32 s13, s3, 0
	global_load_lds_dwordx4 v[0:1], off
	s_add_i32 m0, s83, 0x1c000
	v_lshl_add_u64 v[0:1], s[12:13], 0, v[162:163]
	global_load_lds_dwordx4 v[0:1], off
	v_lshl_add_u64 v[0:1], s[12:13], 0, v[166:167]
	s_add_i32 m0, s83, 0x1e000
	v_and_b32_e32 v181, 15, v8
	global_load_lds_dwordx4 v[0:1], off
	v_bfe_u32 v192, v8, 4, 2
	v_lshlrev_b32_e32 v0, 6, v181
	v_lshlrev_b32_e32 v1, 2, v8
	v_lshl_or_b32 v0, v192, 4, v0
	v_and_b32_e32 v1, 32, v1
	v_bitop3_b32 v2, v0, s7, v1 bitop3:0xde
	v_bitop3_b32 v193, v0, s9, v1 bitop3:0xde
	v_lshlrev_b32_e32 v0, 14, v9
	v_and_b32_e32 v0, 0xffff8000, v0
	v_lshl_add_u32 v0, v10, 11, v0
	v_and_b32_e32 v1, 1, v9
	v_lshl_or_b32 v0, v1, 6, v0
	v_lshl_add_u32 v170, v11, 1, v0
	v_lshlrev_b32_e32 v0, 14, v12
	v_and_b32_e32 v0, 0xffff8000, v0
	v_readlane_b32 s40, v249, 0
	v_readlane_b32 s41, v249, 1
	s_waitcnt vmcnt(6)
	s_cmpk_lt_u32 s6, 0x100
	v_lshl_add_u32 v0, v13, 11, v0
	v_and_b32_e32 v1, 1, v12
	s_cselect_b64 s[40:41], -1, 0
	v_lshl_or_b32 v0, v1, 6, v0
	s_add_i32 s91, 0, 0x10000
	s_add_i32 s92, 0, 0x14000
	v_readlane_b32 s78, v249, 36
	v_readlane_b32 s44, v249, 4
	v_readlane_b32 s46, v249, 6
	v_mov_b32_e32 v171, v169
	v_lshl_add_u32 v172, v14, 1, v0
	v_mov_b32_e32 v173, v169
	v_add_u32_e32 v194, s91, v193
	v_add_u32_e32 v195, s92, v193
	v_add_u32_e32 v196, 0, v2
	v_mov_b32_e32 v197, 0x358637bd
	s_mov_b32 s93, 0x800000
	s_movk_i32 s94, 0x2c00
	s_movk_i32 s95, 0x5800
	s_mov_b64 s[42:43], 0x2c00
	s_movk_i32 s96, 0x1600
	v_readlane_b32 s79, v249, 37
	v_readlane_b32 s45, v249, 5
	v_readlane_b32 s47, v249, 7
	v_readlane_b32 s48, v249, 8
	v_readlane_b32 s49, v249, 9
	s_barrier
	v_mov_b32_e32 v252, 0xc0135761
	v_mov_b32_e32 v253, 0xc0135761
	v_mov_b32_e32 v254, 0xbdd2d3e7
	v_mov_b32_e32 v255, 0xbdd2d3e7
	s_branch .LBB0_1211

.LBB0_1300:
	s_or_b64 exec, exec, s[8:9]
	v_readlane_b32 s0, v249, 52
	v_readlane_b32 s1, v249, 53
	v_readlane_b32 s56, v250, 60
	v_readlane_b32 s58, v250, 62
	v_lshl_add_u64 v[128:129], v[182:183], 2, s[0:1]
	global_load_dword v168, v[128:129], off
	global_load_dword v205, v[128:129], off offset:64
	global_load_dword v204, v[128:129], off offset:128
	global_load_dword v203, v[128:129], off offset:192
	global_load_dword v202, v[128:129], off offset:512
	global_load_dword v201, v[128:129], off offset:576
	global_load_dword v200, v[128:129], off offset:640
	global_load_dword v187, v[128:129], off offset:704
	v_readlane_b32 s59, v250, 63
	v_readlane_b32 s60, v249, 0
	v_readlane_b32 s61, v249, 1
	v_readlane_b32 s62, v249, 2
	v_readlane_b32 s63, v249, 3
	v_readlane_b32 s64, v249, 4
	v_readlane_b32 s65, v249, 5
	v_lshlrev_b64 v[156:157], 2, v[174:175]
	s_mov_b64 s[58:59], s[62:63]
	s_mov_b64 s[60:61], s[64:65]
	v_lshl_add_u64 v[188:189], s[58:59], 0, v[156:157]
	v_lshl_add_u64 v[128:129], s[28:29], 0, v[156:157]
	v_lshl_add_u64 v[130:131], s[30:31], 0, v[156:157]
	v_lshl_add_u64 v[190:191], s[60:61], 0, v[156:157]
	v_lshl_add_u64 v[144:145], s[18:19], 0, v[156:157]
	v_lshl_add_u64 v[146:147], s[34:35], 0, v[156:157]
	v_lshl_add_u64 v[148:149], s[36:37], 0, v[156:157]
	v_lshl_add_u64 v[156:157], s[20:21], 0, v[156:157]
	global_load_dwordx4 v[136:139], v[188:189], off
	global_load_dwordx4 v[132:135], v[128:129], off
	s_nop 0
	global_load_dwordx4 v[128:131], v[130:131], off
	s_lshl_b32 s0, s45, 13
	global_load_dwordx4 v[140:143], v[190:191], off
	global_load_dwordx4 v[152:155], v[144:145], off
	s_nop 0
	global_load_dwordx4 v[144:147], v[146:147], off
	s_lshl_b32 s1, s47, 11
	global_load_dwordx4 v[148:151], v[148:149], off
	s_add_i32 s0, s0, 0
	global_load_dwordx4 v[156:159], v[156:157], off
	v_lshlrev_b32_e32 v206, 4, v186
	s_add_i32 s0, s0, s1
	v_and_b32_e32 v183, 6, v186
	v_add_u32_e32 v185, 0x1f0, v206
	s_add_i32 s0, s0, 0x20000
	v_cmp_eq_u32_e32 vcc, 0, v183
	v_and_b32_e32 v183, 0x1f0, v185
	v_lshl_add_u32 v198, v198, 4, s0
	v_cndmask_b32_e64 v222, 0, 1, vcc
	v_cndmask_b32_e64 v199, v199, v222, s[6:7]
	v_add_u32_e32 v207, 0x1e0, v206
	v_and_b32_e32 v199, 1, v199
	v_and_b32_e32 v207, 0x1f0, v207
	v_readlane_b32 s2, v249, 54
	v_readlane_b32 s3, v249, 55
	v_readlane_b32 s57, v250, 61
	v_readlane_b32 s66, v249, 6
	v_readlane_b32 s67, v249, 7
	v_readlane_b32 s68, v249, 8
	v_readlane_b32 s69, v249, 9
	v_readlane_b32 s70, v249, 10
	v_readlane_b32 s71, v249, 11
	s_waitcnt vmcnt(0)
	v_fmamk_f32 v168, v168, 0x3a800000, v197
	v_mul_f32_e32 v185, 0x4b800000, v168
	v_cmp_gt_f32_e64 s[0:1], s93, v168
	s_nop 1
	v_cndmask_b32_e64 v168, v168, v185, s[0:1]
	v_rsq_f32_e32 v223, v168
	v_lshl_add_u32 v168, v186, 6, v198
	v_lshl_add_u32 v185, v183, 2, v198
	v_lshl_add_u32 v183, v207, 2, v198
	v_mul_f32_e32 v186, 0x45800000, v223
	v_cndmask_b32_e64 v186, v223, v186, s[0:1]
	v_pk_mul_f32 v[126:127], v[126:127], v[186:187] op_sel_hi:[1,0]
	v_pk_mul_f32 v[124:125], v[124:125], v[186:187] op_sel_hi:[1,0]
	v_pk_mul_f32 v[122:123], v[122:123], v[186:187] op_sel_hi:[1,0]
	v_pk_mul_f32 v[120:121], v[120:121], v[186:187] op_sel_hi:[1,0]
	ds_write_b128 v168, v[124:127]
	ds_write_b128 v168, v[120:123] offset:16384
	v_cmp_eq_u32_e64 s[0:1], 1, v199
	s_xor_b64 s[8:9], s[0:1], -1
	s_and_saveexec_b64 s[0:1], s[8:9]
	v_readlane_b32 s10, v249, 16
	v_readlane_b32 s11, v249, 17
	s_cbranch_execz .LBB0_1302
	ds_read_b128 v[222:225], v185 offset:16384
	ds_read_b128 v[226:229], v183 offset:16384
	s_waitcnt lgkmcnt(0)
	v_pk_fma_f32 v[228:229], v[154:155], v[228:229], v[158:159]
	v_pk_fma_f32 v[226:227], v[152:153], v[226:227], v[156:157]
	v_pk_fma_f32 v[224:225], v[146:147], v[224:225], v[228:229]
	v_pk_fma_f32 v[222:223], v[144:145], v[222:223], v[226:227]
	v_pk_fma_f32 v[226:227], v[122:123], v[150:151], v[224:225]
	v_pk_fma_f32 v[228:229], v[120:121], v[148:149], v[222:223]
	ds_read_b128 v[120:123], v185
	ds_read_b128 v[222:225], v183
	s_waitcnt lgkmcnt(0)
	v_pk_fma_f32 v[222:223], v[136:137], v[222:223], v[140:141]
	s_nop 0
	v_pk_fma_f32 v[120:121], v[132:133], v[120:121], v[222:223]
	v_pk_fma_f32 v[224:225], v[138:139], v[224:225], v[142:143]
	v_pk_fma_f32 v[120:121], v[128:129], v[124:125], v[120:121]
	v_pk_fma_f32 v[122:123], v[134:135], v[122:123], v[224:225]
	v_pk_mul_f32 v[124:125], v[228:229], v[228:229]
	v_pk_fma_f32 v[124:125], v[124:125], v[254:255], v[252:253]
	v_pk_mul_f32 v[124:125], v[124:125], v[228:229]
	v_exp_f32_e32 v124, v124
	v_exp_f32_e32 v125, v125
	v_add_f32_e32 v124, 1.0, v124
	v_add_f32_e32 v125, 1.0, v125
	v_rcp_f32_e32 v124, v124
	v_rcp_f32_e32 v125, v125
	s_nop 0
	v_pk_fma_f32 v[122:123], v[130:131], v[126:127], v[122:123]
	v_pk_mul_f32 v[124:125], v[228:229], v[124:125]
	s_nop 0
	v_pk_mul_f32 v[120:121], v[120:121], v[124:125]
	s_nop 0
	v_cvt_pk_bf16_f32 v120, v120, v121
	s_nop 0
	s_nop 0
	v_pk_mul_f32 v[124:125], v[226:227], v[226:227]
	v_pk_fma_f32 v[124:125], v[124:125], v[254:255], v[252:253]
	v_pk_mul_f32 v[124:125], v[124:125], v[226:227]
	v_exp_f32_e32 v124, v124
	v_exp_f32_e32 v125, v125
	v_add_f32_e32 v124, 1.0, v124
	v_add_f32_e32 v125, 1.0, v125
	v_rcp_f32_e32 v124, v124
	v_rcp_f32_e32 v125, v125
	s_nop 0
	s_nop 0
	v_pk_mul_f32 v[124:125], v[226:227], v[124:125]
	s_nop 0
	v_pk_mul_f32 v[122:123], v[122:123], v[124:125]
	s_nop 0
	v_cvt_pk_bf16_f32 v121, v122, v123
	v_mov_b64_e32 v[122:123], s[10:11]
	v_mad_i64_i32 v[122:123], s[2:3], v182, s96, v[122:123]
	v_lshl_add_u64 v[122:123], v[174:175], 1, v[122:123]
	global_store_dwordx2 v[122:123], v[120:121], off
.LBB0_1302:
	s_or_b64 exec, exec, s[0:1]
	v_fmamk_f32 v120, v205, 0x3a800000, v197
	v_mul_f32_e32 v121, 0x4b800000, v120
	v_cmp_gt_f32_e64 s[0:1], s93, v120
	v_add_u32_e32 v124, 16, v182
	s_nop 0
	v_cndmask_b32_e64 v120, v120, v121, s[0:1]
	v_rsq_f32_e32 v120, v120
	s_nop 0
	v_mul_f32_e32 v121, 0x45800000, v120
	v_cndmask_b32_e64 v120, v120, v121, s[0:1]
	v_pk_mul_f32 v[118:119], v[118:119], v[120:121] op_sel_hi:[1,0]
	v_pk_mul_f32 v[116:117], v[116:117], v[120:121] op_sel_hi:[1,0]
	v_pk_mul_f32 v[114:115], v[114:115], v[120:121] op_sel_hi:[1,0]
	v_pk_mul_f32 v[112:113], v[112:113], v[120:121] op_sel_hi:[1,0]
	v_add_u32_e32 v121, 0xf0, v206
	ds_write_b128 v168, v[116:119] offset:1024
	ds_write_b128 v168, v[112:115] offset:17408
	v_and_b32_e32 v121, 0x1f0, v121
	v_lshl_add_u32 v122, v121, 2, v198
	v_add_u32_e32 v121, 0xe0, v206
	v_and_b32_e32 v121, 0x1f0, v121
	s_and_b64 s[0:1], s[6:7], vcc
	v_lshl_add_u32 v123, v121, 2, v198
	s_xor_b64 s[0:1], s[0:1], -1
	s_and_saveexec_b64 s[2:3], s[0:1]
	s_cbranch_execz .LBB0_1304
	ds_read_b128 v[222:225], v122 offset:16384
	ds_read_b128 v[226:229], v123 offset:16384
	s_waitcnt lgkmcnt(0)
	v_pk_fma_f32 v[126:127], v[154:155], v[228:229], v[158:159]
	v_pk_fma_f32 v[198:199], v[152:153], v[226:227], v[156:157]
	v_pk_fma_f32 v[126:127], v[146:147], v[224:225], v[126:127]
	v_pk_fma_f32 v[198:199], v[144:145], v[222:223], v[198:199]
	v_pk_fma_f32 v[126:127], v[114:115], v[150:151], v[126:127]
	v_pk_fma_f32 v[198:199], v[112:113], v[148:149], v[198:199]
	ds_read_b128 v[112:115], v122
	ds_read_b128 v[222:225], v123
	s_waitcnt lgkmcnt(0)
	v_pk_fma_f32 v[222:223], v[136:137], v[222:223], v[140:141]
	s_nop 0
	v_pk_fma_f32 v[112:113], v[132:133], v[112:113], v[222:223]
	v_pk_fma_f32 v[206:207], v[138:139], v[224:225], v[142:143]
	v_pk_fma_f32 v[112:113], v[128:129], v[116:117], v[112:113]
	v_pk_fma_f32 v[114:115], v[134:135], v[114:115], v[206:207]
	v_pk_mul_f32 v[116:117], v[198:199], v[198:199]
	v_pk_fma_f32 v[116:117], v[116:117], v[254:255], v[252:253]
	v_pk_mul_f32 v[116:117], v[116:117], v[198:199]
	v_exp_f32_e32 v116, v116
	v_exp_f32_e32 v117, v117
	v_add_f32_e32 v116, 1.0, v116
	v_add_f32_e32 v117, 1.0, v117
	v_rcp_f32_e32 v116, v116
	v_rcp_f32_e32 v117, v117
	s_nop 0
	v_pk_fma_f32 v[114:115], v[130:131], v[118:119], v[114:115]
	v_pk_mul_f32 v[116:117], v[198:199], v[116:117]
	s_nop 0
	v_pk_mul_f32 v[112:113], v[112:113], v[116:117]
	s_nop 0
	v_cvt_pk_bf16_f32 v112, v112, v113
	s_nop 0
	s_nop 0
	v_pk_mul_f32 v[116:117], v[126:127], v[126:127]
	v_pk_fma_f32 v[116:117], v[116:117], v[254:255], v[252:253]
	v_pk_mul_f32 v[116:117], v[116:117], v[126:127]
	v_exp_f32_e32 v116, v116
	v_exp_f32_e32 v117, v117
	v_add_f32_e32 v116, 1.0, v116
	v_add_f32_e32 v117, 1.0, v117
	v_rcp_f32_e32 v116, v116
	v_rcp_f32_e32 v117, v117
	s_nop 0
	s_nop 0
	v_pk_mul_f32 v[116:117], v[126:127], v[116:117]
	s_nop 0
	v_pk_mul_f32 v[114:115], v[114:115], v[116:117]
	s_nop 0
	v_cvt_pk_bf16_f32 v113, v114, v115
	v_mov_b64_e32 v[114:115], s[10:11]
	v_mad_i64_i32 v[114:115], s[6:7], v124, s96, v[114:115]
	v_lshl_add_u64 v[114:115], v[174:175], 1, v[114:115]
	global_store_dwordx2 v[114:115], v[112:113], off
.LBB0_1304:
	s_or_b64 exec, exec, s[2:3]
	v_fmamk_f32 v112, v204, 0x3a800000, v197
	v_mul_f32_e32 v113, 0x4b800000, v112
	v_cmp_gt_f32_e32 vcc, s93, v112
	v_add_u32_e32 v114, 32, v182
	s_nop 0
	v_cndmask_b32_e32 v112, v112, v113, vcc
	v_rsq_f32_e32 v112, v112
	s_nop 0
	v_mul_f32_e32 v113, 0x45800000, v112
	v_cndmask_b32_e32 v112, v112, v113, vcc
	v_pk_mul_f32 v[110:111], v[110:111], v[112:113] op_sel_hi:[1,0]
	v_pk_mul_f32 v[108:109], v[108:109], v[112:113] op_sel_hi:[1,0]
	v_pk_mul_f32 v[106:107], v[106:107], v[112:113] op_sel_hi:[1,0]
	v_pk_mul_f32 v[104:105], v[104:105], v[112:113] op_sel_hi:[1,0]
	ds_write_b128 v168, v[108:111]
	ds_write_b128 v168, v[104:107] offset:16384
	s_and_saveexec_b64 s[2:3], s[0:1]
	s_cbranch_execz .LBB0_1306
	ds_read_b128 v[116:119], v185 offset:16384
	ds_read_b128 v[204:207], v183 offset:16384
	s_waitcnt lgkmcnt(0)
	v_pk_fma_f32 v[126:127], v[154:155], v[206:207], v[158:159]
	v_pk_fma_f32 v[198:199], v[152:153], v[204:205], v[156:157]
	v_pk_fma_f32 v[118:119], v[146:147], v[118:119], v[126:127]
	v_pk_fma_f32 v[116:117], v[144:145], v[116:117], v[198:199]
	v_pk_fma_f32 v[126:127], v[106:107], v[150:151], v[118:119]
	v_pk_fma_f32 v[198:199], v[104:105], v[148:149], v[116:117]
	ds_read_b128 v[104:107], v185
	ds_read_b128 v[116:119], v183
	s_waitcnt lgkmcnt(0)
	v_pk_fma_f32 v[116:117], v[136:137], v[116:117], v[140:141]
	s_nop 0
	v_pk_fma_f32 v[104:105], v[132:133], v[104:105], v[116:117]
	v_pk_fma_f32 v[118:119], v[138:139], v[118:119], v[142:143]
	v_pk_fma_f32 v[104:105], v[128:129], v[108:109], v[104:105]
	v_pk_fma_f32 v[106:107], v[134:135], v[106:107], v[118:119]
	v_pk_mul_f32 v[108:109], v[198:199], v[198:199]
	v_pk_fma_f32 v[108:109], v[108:109], v[254:255], v[252:253]
	v_pk_mul_f32 v[108:109], v[108:109], v[198:199]
	v_exp_f32_e32 v108, v108
	v_exp_f32_e32 v109, v109
	v_add_f32_e32 v108, 1.0, v108
	v_add_f32_e32 v109, 1.0, v109
	v_rcp_f32_e32 v108, v108
	v_rcp_f32_e32 v109, v109
	s_nop 0
	v_pk_fma_f32 v[106:107], v[130:131], v[110:111], v[106:107]
	v_pk_mul_f32 v[108:109], v[198:199], v[108:109]
	s_nop 0
	v_pk_mul_f32 v[104:105], v[104:105], v[108:109]
	s_nop 0
	v_cvt_pk_bf16_f32 v104, v104, v105
	s_nop 0
	s_nop 0
	v_pk_mul_f32 v[108:109], v[126:127], v[126:127]
	v_pk_fma_f32 v[108:109], v[108:109], v[254:255], v[252:253]
	v_pk_mul_f32 v[108:109], v[108:109], v[126:127]
	v_exp_f32_e32 v108, v108
	v_exp_f32_e32 v109, v109
	v_add_f32_e32 v108, 1.0, v108
	v_add_f32_e32 v109, 1.0, v109
	v_rcp_f32_e32 v108, v108
	v_rcp_f32_e32 v109, v109
	s_nop 0
	s_nop 0
	v_pk_mul_f32 v[108:109], v[126:127], v[108:109]
	s_nop 0
	v_pk_mul_f32 v[106:107], v[106:107], v[108:109]
	s_nop 0
	v_cvt_pk_bf16_f32 v105, v106, v107
	v_mov_b64_e32 v[106:107], s[10:11]
	v_mad_i64_i32 v[106:107], s[6:7], v114, s96, v[106:107]
	v_lshl_add_u64 v[106:107], v[174:175], 1, v[106:107]
	global_store_dwordx2 v[106:107], v[104:105], off
.LBB0_1306:
	s_or_b64 exec, exec, s[2:3]
	v_fmamk_f32 v104, v203, 0x3a800000, v197
	v_mul_f32_e32 v105, 0x4b800000, v104
	v_cmp_gt_f32_e32 vcc, s93, v104
	v_add_u32_e32 v106, 48, v182
	s_nop 0
	v_cndmask_b32_e32 v104, v104, v105, vcc
	v_rsq_f32_e32 v104, v104
	s_nop 0
	v_mul_f32_e32 v105, 0x45800000, v104
	v_cndmask_b32_e32 v104, v104, v105, vcc
	v_pk_mul_f32 v[102:103], v[102:103], v[104:105] op_sel_hi:[1,0]
	v_pk_mul_f32 v[100:101], v[100:101], v[104:105] op_sel_hi:[1,0]
	v_pk_mul_f32 v[98:99], v[98:99], v[104:105] op_sel_hi:[1,0]
	v_pk_mul_f32 v[96:97], v[96:97], v[104:105] op_sel_hi:[1,0]
	ds_write_b128 v168, v[100:103] offset:1024
	ds_write_b128 v168, v[96:99] offset:17408
	s_and_saveexec_b64 s[2:3], s[0:1]
	s_cbranch_execz .LBB0_1308
	ds_read_b128 v[108:111], v122 offset:16384
	ds_read_b128 v[116:119], v123 offset:16384
	s_waitcnt lgkmcnt(0)
	v_pk_fma_f32 v[118:119], v[154:155], v[118:119], v[158:159]
	v_pk_fma_f32 v[116:117], v[152:153], v[116:117], v[156:157]
	v_pk_fma_f32 v[110:111], v[146:147], v[110:111], v[118:119]
	v_pk_fma_f32 v[108:109], v[144:145], v[108:109], v[116:117]
	v_pk_fma_f32 v[116:117], v[98:99], v[150:151], v[110:111]
	v_pk_fma_f32 v[118:119], v[96:97], v[148:149], v[108:109]
	ds_read_b128 v[96:99], v122
	ds_read_b128 v[108:111], v123
	s_waitcnt lgkmcnt(0)
	v_pk_fma_f32 v[108:109], v[136:137], v[108:109], v[140:141]
	s_nop 0
	v_pk_fma_f32 v[96:97], v[132:133], v[96:97], v[108:109]
	v_pk_fma_f32 v[110:111], v[138:139], v[110:111], v[142:143]
	v_pk_fma_f32 v[96:97], v[128:129], v[100:101], v[96:97]
	v_pk_fma_f32 v[98:99], v[134:135], v[98:99], v[110:111]
	v_pk_mul_f32 v[100:101], v[118:119], v[118:119]
	v_pk_fma_f32 v[100:101], v[100:101], v[254:255], v[252:253]
	v_pk_mul_f32 v[100:101], v[100:101], v[118:119]
	v_exp_f32_e32 v100, v100
	v_exp_f32_e32 v101, v101
	v_add_f32_e32 v100, 1.0, v100
	v_add_f32_e32 v101, 1.0, v101
	v_rcp_f32_e32 v100, v100
	v_rcp_f32_e32 v101, v101
	s_nop 0
	v_pk_fma_f32 v[98:99], v[130:131], v[102:103], v[98:99]
	v_pk_mul_f32 v[100:101], v[118:119], v[100:101]
	s_nop 0
	v_pk_mul_f32 v[96:97], v[96:97], v[100:101]
	s_nop 0
	v_cvt_pk_bf16_f32 v96, v96, v97
	s_nop 0
	s_nop 0
	v_pk_mul_f32 v[100:101], v[116:117], v[116:117]
	v_pk_fma_f32 v[100:101], v[100:101], v[254:255], v[252:253]
	v_pk_mul_f32 v[100:101], v[100:101], v[116:117]
	v_exp_f32_e32 v100, v100
	v_exp_f32_e32 v101, v101
	v_add_f32_e32 v100, 1.0, v100
	v_add_f32_e32 v101, 1.0, v101
	v_rcp_f32_e32 v100, v100
	v_rcp_f32_e32 v101, v101
	s_nop 0
	s_nop 0
	v_pk_mul_f32 v[100:101], v[116:117], v[100:101]
	s_nop 0
	v_pk_mul_f32 v[98:99], v[98:99], v[100:101]
	s_nop 0
	v_cvt_pk_bf16_f32 v97, v98, v99
	v_mov_b64_e32 v[98:99], s[10:11]
	v_mad_i64_i32 v[98:99], s[6:7], v106, s96, v[98:99]
	v_lshl_add_u64 v[98:99], v[174:175], 1, v[98:99]
	global_store_dwordx2 v[98:99], v[96:97], off
.LBB0_1308:
	s_or_b64 exec, exec, s[2:3]
	v_fmamk_f32 v96, v202, 0x3a800000, v197
	v_mul_f32_e32 v97, 0x4b800000, v96
	v_cmp_gt_f32_e32 vcc, s93, v96
	s_nop 1
	v_cndmask_b32_e32 v96, v96, v97, vcc
	v_rsq_f32_e32 v96, v96
	s_nop 0
	v_mul_f32_e32 v97, 0x45800000, v96
	v_cndmask_b32_e32 v96, v96, v97, vcc
	v_pk_mul_f32 v[94:95], v[94:95], v[96:97] op_sel_hi:[1,0]
	v_pk_mul_f32 v[92:93], v[92:93], v[96:97] op_sel_hi:[1,0]
	v_pk_mul_f32 v[90:91], v[90:91], v[96:97] op_sel_hi:[1,0]
	v_pk_mul_f32 v[88:89], v[88:89], v[96:97] op_sel_hi:[1,0]
	ds_write_b128 v168, v[92:95]
	ds_write_b128 v168, v[88:91] offset:16384
	s_and_saveexec_b64 s[2:3], s[8:9]
	s_cbranch_execz .LBB0_1310
	ds_read_b128 v[98:101], v185 offset:16384
	ds_read_b128 v[108:111], v183 offset:16384
	s_waitcnt lgkmcnt(0)
	v_pk_fma_f32 v[102:103], v[154:155], v[110:111], v[158:159]
	v_pk_fma_f32 v[108:109], v[152:153], v[108:109], v[156:157]
	v_pk_fma_f32 v[100:101], v[146:147], v[100:101], v[102:103]
	v_pk_fma_f32 v[98:99], v[144:145], v[98:99], v[108:109]
	v_pk_fma_f32 v[102:103], v[150:151], v[90:91], v[100:101]
	v_pk_fma_f32 v[108:109], v[148:149], v[88:89], v[98:99]
	ds_read_b128 v[88:91], v185
	ds_read_b128 v[98:101], v183
	s_waitcnt lgkmcnt(0)
	v_pk_fma_f32 v[98:99], v[136:137], v[98:99], v[140:141]
	s_nop 0
	v_pk_fma_f32 v[88:89], v[132:133], v[88:89], v[98:99]
	v_pk_fma_f32 v[100:101], v[138:139], v[100:101], v[142:143]
	v_pk_fma_f32 v[88:89], v[128:129], v[92:93], v[88:89]
	v_pk_fma_f32 v[90:91], v[134:135], v[90:91], v[100:101]
	v_pk_mul_f32 v[92:93], v[108:109], v[108:109]
	v_pk_fma_f32 v[92:93], v[92:93], v[254:255], v[252:253]
	v_pk_mul_f32 v[92:93], v[92:93], v[108:109]
	v_exp_f32_e32 v92, v92
	v_exp_f32_e32 v93, v93
	v_add_f32_e32 v92, 1.0, v92
	v_add_f32_e32 v93, 1.0, v93
	v_rcp_f32_e32 v92, v92
	v_rcp_f32_e32 v93, v93
	s_nop 0
	v_pk_fma_f32 v[90:91], v[130:131], v[94:95], v[90:91]
	v_pk_mul_f32 v[92:93], v[108:109], v[92:93]
	s_nop 0
	v_pk_mul_f32 v[88:89], v[88:89], v[92:93]
	s_nop 0
	v_cvt_pk_bf16_f32 v88, v88, v89
	s_nop 0
	s_nop 0
	v_pk_mul_f32 v[92:93], v[102:103], v[102:103]
	v_pk_fma_f32 v[92:93], v[92:93], v[254:255], v[252:253]
	v_pk_mul_f32 v[92:93], v[92:93], v[102:103]
	v_exp_f32_e32 v92, v92
	v_exp_f32_e32 v93, v93
	v_add_f32_e32 v92, 1.0, v92
	v_add_f32_e32 v93, 1.0, v93
	v_rcp_f32_e32 v92, v92
	v_rcp_f32_e32 v93, v93
	s_nop 0
	s_nop 0
	v_pk_mul_f32 v[92:93], v[102:103], v[92:93]
	s_nop 0
	v_pk_mul_f32 v[90:91], v[90:91], v[92:93]
	s_nop 0
	v_cvt_pk_bf16_f32 v89, v90, v91
	v_mov_b64_e32 v[90:91], s[10:11]
	v_mad_i64_i32 v[90:91], s[6:7], v184, s96, v[90:91]
	v_lshl_add_u64 v[90:91], v[174:175], 1, v[90:91]
	global_store_dwordx2 v[90:91], v[88:89], off
.LBB0_1310:
	s_or_b64 exec, exec, s[2:3]
	v_fmamk_f32 v88, v201, 0x3a800000, v197
	v_mul_f32_e32 v89, 0x4b800000, v88
	v_cmp_gt_f32_e32 vcc, s93, v88
	v_add_u32_e32 v101, 16, v184
	s_nop 0
	v_cndmask_b32_e32 v88, v88, v89, vcc
	v_rsq_f32_e32 v88, v88
	s_nop 0
	v_mul_f32_e32 v89, 0x45800000, v88
	v_cndmask_b32_e32 v98, v88, v89, vcc
	v_pk_mul_f32 v[86:87], v[86:87], v[98:99] op_sel_hi:[1,0]
	v_pk_mul_f32 v[84:85], v[84:85], v[98:99] op_sel_hi:[1,0]
	v_pk_mul_f32 v[82:83], v[82:83], v[98:99] op_sel_hi:[1,0]
	v_pk_mul_f32 v[80:81], v[80:81], v[98:99] op_sel_hi:[1,0]
	ds_write_b128 v168, v[84:87] offset:1024
	ds_write_b128 v168, v[80:83] offset:17408
	s_and_saveexec_b64 s[2:3], s[0:1]
	s_cbranch_execz .LBB0_1312
	ds_read_b128 v[88:91], v122 offset:16384
	ds_read_b128 v[92:95], v123 offset:16384
	s_waitcnt lgkmcnt(0)
	v_pk_fma_f32 v[94:95], v[154:155], v[94:95], v[158:159]
	v_pk_fma_f32 v[92:93], v[152:153], v[92:93], v[156:157]
	v_pk_fma_f32 v[90:91], v[146:147], v[90:91], v[94:95]
	v_pk_fma_f32 v[88:89], v[144:145], v[88:89], v[92:93]
	v_pk_fma_f32 v[92:93], v[150:151], v[82:83], v[90:91]
	v_pk_fma_f32 v[94:95], v[148:149], v[80:81], v[88:89]
	ds_read_b128 v[80:83], v122
	ds_read_b128 v[88:91], v123
	s_waitcnt lgkmcnt(0)
	v_pk_fma_f32 v[88:89], v[136:137], v[88:89], v[140:141]
	s_nop 0
	v_pk_fma_f32 v[80:81], v[132:133], v[80:81], v[88:89]
	v_pk_fma_f32 v[90:91], v[138:139], v[90:91], v[142:143]
	v_pk_fma_f32 v[80:81], v[128:129], v[84:85], v[80:81]
	v_pk_fma_f32 v[82:83], v[134:135], v[82:83], v[90:91]
	v_pk_mul_f32 v[84:85], v[94:95], v[94:95]
	v_pk_fma_f32 v[84:85], v[84:85], v[254:255], v[252:253]
	v_pk_mul_f32 v[84:85], v[84:85], v[94:95]
	v_exp_f32_e32 v84, v84
	v_exp_f32_e32 v85, v85
	v_add_f32_e32 v84, 1.0, v84
	v_add_f32_e32 v85, 1.0, v85
	v_rcp_f32_e32 v84, v84
	v_rcp_f32_e32 v85, v85
	s_nop 0
	v_pk_fma_f32 v[82:83], v[130:131], v[86:87], v[82:83]
	v_pk_mul_f32 v[84:85], v[94:95], v[84:85]
	s_nop 0
	v_pk_mul_f32 v[80:81], v[80:81], v[84:85]
	s_nop 0
	v_cvt_pk_bf16_f32 v80, v80, v81
	s_nop 0
	s_nop 0
	v_pk_mul_f32 v[84:85], v[92:93], v[92:93]
	v_pk_fma_f32 v[84:85], v[84:85], v[254:255], v[252:253]
	v_pk_mul_f32 v[84:85], v[84:85], v[92:93]
	v_exp_f32_e32 v84, v84
	v_exp_f32_e32 v85, v85
	v_add_f32_e32 v84, 1.0, v84
	v_add_f32_e32 v85, 1.0, v85
	v_rcp_f32_e32 v84, v84
	v_rcp_f32_e32 v85, v85
	s_nop 0
	s_nop 0
	v_pk_mul_f32 v[84:85], v[92:93], v[84:85]
	s_nop 0
	v_pk_mul_f32 v[82:83], v[82:83], v[84:85]
	s_nop 0
	v_cvt_pk_bf16_f32 v81, v82, v83
	v_mov_b64_e32 v[82:83], s[10:11]
	v_mad_i64_i32 v[82:83], s[6:7], v101, s96, v[82:83]
	v_lshl_add_u64 v[82:83], v[174:175], 1, v[82:83]
	global_store_dwordx2 v[82:83], v[80:81], off
.LBB0_1312:
	s_or_b64 exec, exec, s[2:3]
	v_fmamk_f32 v80, v200, 0x3a800000, v197
	v_mul_f32_e32 v81, 0x4b800000, v80
	v_cmp_gt_f32_e32 vcc, s93, v80
	v_add_u32_e32 v103, 32, v184
	s_nop 0
	v_cndmask_b32_e32 v80, v80, v81, vcc
	v_rsq_f32_e32 v80, v80
	s_nop 0
	v_mul_f32_e32 v81, 0x45800000, v80
	v_cndmask_b32_e32 v100, v80, v81, vcc
	v_pk_mul_f32 v[78:79], v[78:79], v[100:101] op_sel_hi:[1,0]
	v_pk_mul_f32 v[76:77], v[76:77], v[100:101] op_sel_hi:[1,0]
	v_pk_mul_f32 v[74:75], v[74:75], v[100:101] op_sel_hi:[1,0]
	v_pk_mul_f32 v[72:73], v[72:73], v[100:101] op_sel_hi:[1,0]
	ds_write_b128 v168, v[76:79]
	ds_write_b128 v168, v[72:75] offset:16384
	s_and_saveexec_b64 s[2:3], s[0:1]
	s_cbranch_execz .LBB0_1314
	ds_read_b128 v[80:83], v185 offset:16384
	ds_read_b128 v[84:87], v183 offset:16384
	s_waitcnt lgkmcnt(0)
	v_pk_fma_f32 v[86:87], v[154:155], v[86:87], v[158:159]
	v_pk_fma_f32 v[84:85], v[152:153], v[84:85], v[156:157]
	v_pk_fma_f32 v[82:83], v[146:147], v[82:83], v[86:87]
	v_pk_fma_f32 v[80:81], v[144:145], v[80:81], v[84:85]
	v_pk_fma_f32 v[84:85], v[150:151], v[74:75], v[82:83]
	v_pk_fma_f32 v[86:87], v[148:149], v[72:73], v[80:81]
	ds_read_b128 v[72:75], v185
	ds_read_b128 v[80:83], v183
	s_waitcnt lgkmcnt(0)
	v_pk_fma_f32 v[80:81], v[136:137], v[80:81], v[140:141]
	s_nop 0
	v_pk_fma_f32 v[72:73], v[132:133], v[72:73], v[80:81]
	v_pk_fma_f32 v[82:83], v[138:139], v[82:83], v[142:143]
	v_pk_fma_f32 v[72:73], v[128:129], v[76:77], v[72:73]
	v_pk_fma_f32 v[74:75], v[134:135], v[74:75], v[82:83]
	v_pk_mul_f32 v[76:77], v[86:87], v[86:87]
	v_pk_fma_f32 v[76:77], v[76:77], v[254:255], v[252:253]
	v_pk_mul_f32 v[76:77], v[76:77], v[86:87]
	v_exp_f32_e32 v76, v76
	v_exp_f32_e32 v77, v77
	v_add_f32_e32 v76, 1.0, v76
	v_add_f32_e32 v77, 1.0, v77
	v_rcp_f32_e32 v76, v76
	v_rcp_f32_e32 v77, v77
	s_nop 0
	v_pk_fma_f32 v[74:75], v[130:131], v[78:79], v[74:75]
	v_pk_mul_f32 v[76:77], v[86:87], v[76:77]
	s_nop 0
	v_pk_mul_f32 v[72:73], v[72:73], v[76:77]
	s_nop 0
	v_cvt_pk_bf16_f32 v72, v72, v73
	s_nop 0
	s_nop 0
	v_pk_mul_f32 v[76:77], v[84:85], v[84:85]
	v_pk_fma_f32 v[76:77], v[76:77], v[254:255], v[252:253]
	v_pk_mul_f32 v[76:77], v[76:77], v[84:85]
	v_exp_f32_e32 v76, v76
	v_exp_f32_e32 v77, v77
	v_add_f32_e32 v76, 1.0, v76
	v_add_f32_e32 v77, 1.0, v77
	v_rcp_f32_e32 v76, v76
	v_rcp_f32_e32 v77, v77
	s_nop 0
	s_nop 0
	v_pk_mul_f32 v[76:77], v[84:85], v[76:77]
	s_nop 0
	v_pk_mul_f32 v[74:75], v[74:75], v[76:77]
	s_nop 0
	v_cvt_pk_bf16_f32 v73, v74, v75
	v_mov_b64_e32 v[74:75], s[10:11]
	v_mad_i64_i32 v[74:75], s[6:7], v103, s96, v[74:75]
	v_lshl_add_u64 v[74:75], v[174:175], 1, v[74:75]
	global_store_dwordx2 v[74:75], v[72:73], off
.LBB0_1314:
	s_or_b64 exec, exec, s[2:3]
	v_fmamk_f32 v72, v187, 0x3a800000, v197
	v_mul_f32_e32 v73, 0x4b800000, v72
	v_cmp_gt_f32_e32 vcc, s93, v72
	v_add_u32_e32 v107, 48, v184
	s_nop 0
	v_cndmask_b32_e32 v72, v72, v73, vcc
	v_rsq_f32_e32 v72, v72
	s_nop 0
	v_mul_f32_e32 v73, 0x45800000, v72
	v_cndmask_b32_e32 v102, v72, v73, vcc
	v_pk_mul_f32 v[70:71], v[70:71], v[102:103] op_sel_hi:[1,0]
	v_pk_mul_f32 v[68:69], v[68:69], v[102:103] op_sel_hi:[1,0]
	v_pk_mul_f32 v[66:67], v[66:67], v[102:103] op_sel_hi:[1,0]
	v_pk_mul_f32 v[64:65], v[64:65], v[102:103] op_sel_hi:[1,0]
	ds_write_b128 v168, v[68:71] offset:1024
	ds_write_b128 v168, v[64:67] offset:17408
	s_and_saveexec_b64 s[2:3], s[0:1]
	s_cbranch_execz .LBB0_1316
	ds_read_b128 v[72:75], v122 offset:16384
	ds_read_b128 v[76:79], v123 offset:16384
	s_waitcnt lgkmcnt(0)
	v_pk_fma_f32 v[78:79], v[154:155], v[78:79], v[158:159]
	v_pk_fma_f32 v[76:77], v[152:153], v[76:77], v[156:157]
	v_pk_fma_f32 v[74:75], v[146:147], v[74:75], v[78:79]
	v_pk_fma_f32 v[72:73], v[144:145], v[72:73], v[76:77]
	v_pk_fma_f32 v[76:77], v[150:151], v[66:67], v[74:75]
	v_pk_fma_f32 v[78:79], v[148:149], v[64:65], v[72:73]
	ds_read_b128 v[64:67], v122
	ds_read_b128 v[72:75], v123
	s_waitcnt lgkmcnt(0)
	v_pk_fma_f32 v[72:73], v[136:137], v[72:73], v[140:141]
	s_nop 0
	v_pk_fma_f32 v[64:65], v[132:133], v[64:65], v[72:73]
	v_pk_fma_f32 v[74:75], v[138:139], v[74:75], v[142:143]
	v_pk_fma_f32 v[64:65], v[128:129], v[68:69], v[64:65]
	v_pk_fma_f32 v[66:67], v[134:135], v[66:67], v[74:75]
	v_pk_mul_f32 v[68:69], v[78:79], v[78:79]
	v_pk_fma_f32 v[68:69], v[68:69], v[254:255], v[252:253]
	v_pk_mul_f32 v[68:69], v[68:69], v[78:79]
	v_exp_f32_e32 v68, v68
	v_exp_f32_e32 v69, v69
	v_add_f32_e32 v68, 1.0, v68
	v_add_f32_e32 v69, 1.0, v69
	v_rcp_f32_e32 v68, v68
	v_rcp_f32_e32 v69, v69
	s_nop 0
	v_pk_fma_f32 v[66:67], v[130:131], v[70:71], v[66:67]
	v_pk_mul_f32 v[68:69], v[78:79], v[68:69]
	s_nop 0
	v_pk_mul_f32 v[64:65], v[64:65], v[68:69]
	s_nop 0
	v_cvt_pk_bf16_f32 v64, v64, v65
	s_nop 0
	s_nop 0
	v_pk_mul_f32 v[68:69], v[76:77], v[76:77]
	v_pk_fma_f32 v[68:69], v[68:69], v[254:255], v[252:253]
	v_pk_mul_f32 v[68:69], v[68:69], v[76:77]
	v_exp_f32_e32 v68, v68
	v_exp_f32_e32 v69, v69
	v_add_f32_e32 v68, 1.0, v68
	v_add_f32_e32 v69, 1.0, v69
	v_rcp_f32_e32 v68, v68
	v_rcp_f32_e32 v69, v69
	s_nop 0
	s_nop 0
	v_pk_mul_f32 v[68:69], v[76:77], v[68:69]
	s_nop 0
	v_pk_mul_f32 v[66:67], v[66:67], v[68:69]
	s_nop 0
	v_cvt_pk_bf16_f32 v65, v66, v67
	v_mov_b64_e32 v[66:67], s[10:11]
	v_mad_i64_i32 v[66:67], s[6:7], v107, s96, v[66:67]
	v_lshl_add_u64 v[66:67], v[174:175], 1, v[66:67]
	global_store_dwordx2 v[66:67], v[64:65], off
.LBB0_1316:
	s_or_b64 exec, exec, s[2:3]
	v_or_b32_e32 v64, 4, v174
	v_ashrrev_i32_e32 v65, 31, v64
	v_lshlrev_b64 v[92:93], 2, v[64:65]
	v_lshl_add_u64 v[64:65], s[28:29], 0, v[92:93]
	v_lshl_add_u64 v[66:67], s[30:31], 0, v[92:93]
	global_load_dwordx4 v[72:75], v[188:189], off offset:16
	global_load_dwordx4 v[68:71], v[64:65], off
	s_nop 0
	global_load_dwordx4 v[64:67], v[66:67], off
	s_nop 0
	global_load_dwordx4 v[76:79], v[190:191], off offset:16
	v_lshl_add_u64 v[80:81], s[18:19], 0, v[92:93]
	v_lshl_add_u64 v[82:83], s[34:35], 0, v[92:93]
	v_lshl_add_u64 v[84:85], s[36:37], 0, v[92:93]
	v_lshl_add_u64 v[92:93], s[20:21], 0, v[92:93]
	global_load_dwordx4 v[88:91], v[80:81], off
	s_nop 0
	global_load_dwordx4 v[80:83], v[82:83], off
	v_mov_b32_e32 v187, v186
	global_load_dwordx4 v[84:87], v[84:85], off
	v_mov_b32_e32 v108, v186
	global_load_dwordx4 v[92:95], v[92:93], off
	v_mov_b32_e32 v109, v186
	v_pk_mul_f32 v[62:63], v[62:63], v[108:109]
	v_pk_mul_f32 v[60:61], v[60:61], v[186:187]
	v_pk_mul_f32 v[58:59], v[58:59], v[108:109]
	v_pk_mul_f32 v[56:57], v[56:57], v[186:187]
	ds_write_b128 v168, v[60:63]
	ds_write_b128 v168, v[56:59] offset:16384
	s_and_saveexec_b64 s[2:3], s[8:9]
	s_cbranch_execz .LBB0_1318
	ds_read_b128 v[108:111], v185 offset:16384
	ds_read_b128 v[116:119], v183 offset:16384
	s_waitcnt vmcnt(0) lgkmcnt(0)
	v_pk_fma_f32 v[118:119], v[90:91], v[118:119], v[94:95]
	v_pk_fma_f32 v[116:117], v[88:89], v[116:117], v[92:93]
	v_pk_fma_f32 v[110:111], v[82:83], v[110:111], v[118:119]
	v_pk_fma_f32 v[108:109], v[80:81], v[108:109], v[116:117]
	v_pk_fma_f32 v[116:117], v[58:59], v[86:87], v[110:111]
	v_pk_fma_f32 v[118:119], v[56:57], v[84:85], v[108:109]
	ds_read_b128 v[56:59], v185
	ds_read_b128 v[108:111], v183
	s_waitcnt lgkmcnt(0)
	v_pk_fma_f32 v[108:109], v[72:73], v[108:109], v[76:77]
	s_nop 0
	v_pk_fma_f32 v[56:57], v[68:69], v[56:57], v[108:109]
	v_pk_fma_f32 v[110:111], v[74:75], v[110:111], v[78:79]
	v_pk_fma_f32 v[56:57], v[60:61], v[64:65], v[56:57]
	v_pk_fma_f32 v[58:59], v[70:71], v[58:59], v[110:111]
	v_pk_mul_f32 v[60:61], v[118:119], v[118:119]
	v_pk_fma_f32 v[60:61], v[60:61], v[254:255], v[252:253]
	v_pk_mul_f32 v[60:61], v[60:61], v[118:119]
	v_exp_f32_e32 v60, v60
	v_exp_f32_e32 v61, v61
	v_add_f32_e32 v60, 1.0, v60
	v_add_f32_e32 v61, 1.0, v61
	v_rcp_f32_e32 v60, v60
	v_rcp_f32_e32 v61, v61
	s_nop 0
	v_pk_fma_f32 v[58:59], v[62:63], v[66:67], v[58:59]
	v_pk_mul_f32 v[60:61], v[118:119], v[60:61]
	s_nop 0
	v_pk_mul_f32 v[56:57], v[56:57], v[60:61]
	s_nop 0
	v_cvt_pk_bf16_f32 v56, v56, v57
	s_nop 0
	s_nop 0
	v_pk_mul_f32 v[60:61], v[116:117], v[116:117]
	v_pk_fma_f32 v[60:61], v[60:61], v[254:255], v[252:253]
	v_pk_mul_f32 v[60:61], v[60:61], v[116:117]
	v_exp_f32_e32 v60, v60
	v_exp_f32_e32 v61, v61
	v_add_f32_e32 v60, 1.0, v60
	v_add_f32_e32 v61, 1.0, v61
	v_rcp_f32_e32 v60, v60
	v_rcp_f32_e32 v61, v61
	s_nop 0
	s_nop 0
	v_pk_mul_f32 v[60:61], v[116:117], v[60:61]
	s_nop 0
	v_pk_mul_f32 v[58:59], v[58:59], v[60:61]
	s_nop 0
	v_cvt_pk_bf16_f32 v57, v58, v59
	v_mov_b64_e32 v[58:59], s[10:11]
	v_mad_i64_i32 v[58:59], s[6:7], v182, s96, v[58:59]
	v_lshl_add_u64 v[58:59], v[174:175], 1, v[58:59]
	global_store_dwordx2 v[58:59], v[56:57], off offset:8
.LBB0_1318:
	s_or_b64 exec, exec, s[2:3]
	v_mov_b32_e32 v121, v120
	v_mov_b32_e32 v56, v120
	v_mov_b32_e32 v57, v120
	v_pk_mul_f32 v[54:55], v[54:55], v[56:57]
	v_pk_mul_f32 v[52:53], v[52:53], v[120:121]
	v_pk_mul_f32 v[50:51], v[50:51], v[56:57]
	v_pk_mul_f32 v[48:49], v[48:49], v[120:121]
	ds_write_b128 v168, v[52:55] offset:1024
	ds_write_b128 v168, v[48:51] offset:17408
	s_and_saveexec_b64 s[2:3], s[0:1]
	s_cbranch_execz .LBB0_1320
	ds_read_b128 v[56:59], v122 offset:16384
	ds_read_b128 v[60:63], v123 offset:16384
	s_waitcnt vmcnt(0) lgkmcnt(0)
	v_pk_fma_f32 v[62:63], v[90:91], v[62:63], v[94:95]
	v_pk_fma_f32 v[60:61], v[88:89], v[60:61], v[92:93]
	v_pk_fma_f32 v[58:59], v[82:83], v[58:59], v[62:63]
	v_pk_fma_f32 v[56:57], v[80:81], v[56:57], v[60:61]
	v_pk_fma_f32 v[60:61], v[50:51], v[86:87], v[58:59]
	v_pk_fma_f32 v[62:63], v[48:49], v[84:85], v[56:57]
	ds_read_b128 v[48:51], v122
	ds_read_b128 v[56:59], v123
	s_waitcnt lgkmcnt(0)
	v_pk_fma_f32 v[56:57], v[72:73], v[56:57], v[76:77]
	s_nop 0
	v_pk_fma_f32 v[48:49], v[68:69], v[48:49], v[56:57]
	v_pk_fma_f32 v[58:59], v[74:75], v[58:59], v[78:79]
	v_pk_fma_f32 v[48:49], v[52:53], v[64:65], v[48:49]
	v_pk_fma_f32 v[50:51], v[70:71], v[50:51], v[58:59]
	v_pk_mul_f32 v[52:53], v[62:63], v[62:63]
	v_pk_fma_f32 v[52:53], v[52:53], v[254:255], v[252:253]
	v_pk_mul_f32 v[52:53], v[52:53], v[62:63]
	v_exp_f32_e32 v52, v52
	v_exp_f32_e32 v53, v53
	v_add_f32_e32 v52, 1.0, v52
	v_add_f32_e32 v53, 1.0, v53
	v_rcp_f32_e32 v52, v52
	v_rcp_f32_e32 v53, v53
	s_nop 0
	v_pk_fma_f32 v[50:51], v[54:55], v[66:67], v[50:51]
	v_pk_mul_f32 v[52:53], v[62:63], v[52:53]
	s_nop 0
	v_pk_mul_f32 v[48:49], v[48:49], v[52:53]
	s_nop 0
	v_cvt_pk_bf16_f32 v48, v48, v49
	s_nop 0
	s_nop 0
	v_pk_mul_f32 v[52:53], v[60:61], v[60:61]
	v_pk_fma_f32 v[52:53], v[52:53], v[254:255], v[252:253]
	v_pk_mul_f32 v[52:53], v[52:53], v[60:61]
	v_exp_f32_e32 v52, v52
	v_exp_f32_e32 v53, v53
	v_add_f32_e32 v52, 1.0, v52
	v_add_f32_e32 v53, 1.0, v53
	v_rcp_f32_e32 v52, v52
	v_rcp_f32_e32 v53, v53
	s_nop 0
	s_nop 0
	v_pk_mul_f32 v[52:53], v[60:61], v[52:53]
	s_nop 0
	v_pk_mul_f32 v[50:51], v[50:51], v[52:53]
	s_nop 0
	v_cvt_pk_bf16_f32 v49, v50, v51
	v_mov_b64_e32 v[50:51], s[10:11]
	v_mad_i64_i32 v[50:51], s[6:7], v124, s96, v[50:51]
	v_lshl_add_u64 v[50:51], v[174:175], 1, v[50:51]
	global_store_dwordx2 v[50:51], v[48:49], off offset:8
.LBB0_1320:
	s_or_b64 exec, exec, s[2:3]
	v_mov_b32_e32 v113, v112
	v_mov_b32_e32 v48, v112
	v_mov_b32_e32 v49, v112
	v_pk_mul_f32 v[46:47], v[46:47], v[48:49]
	v_pk_mul_f32 v[44:45], v[44:45], v[112:113]
	v_pk_mul_f32 v[42:43], v[42:43], v[48:49]
	v_pk_mul_f32 v[40:41], v[40:41], v[112:113]
	ds_write_b128 v168, v[44:47]
	ds_write_b128 v168, v[40:43] offset:16384
	s_and_saveexec_b64 s[2:3], s[0:1]
	s_cbranch_execz .LBB0_1322
	ds_read_b128 v[48:51], v185 offset:16384
	ds_read_b128 v[52:55], v183 offset:16384
	s_waitcnt vmcnt(0) lgkmcnt(0)
	v_pk_fma_f32 v[54:55], v[90:91], v[54:55], v[94:95]
	v_pk_fma_f32 v[52:53], v[88:89], v[52:53], v[92:93]
	v_pk_fma_f32 v[50:51], v[82:83], v[50:51], v[54:55]
	v_pk_fma_f32 v[48:49], v[80:81], v[48:49], v[52:53]
	v_pk_fma_f32 v[52:53], v[42:43], v[86:87], v[50:51]
	v_pk_fma_f32 v[54:55], v[40:41], v[84:85], v[48:49]
	ds_read_b128 v[40:43], v185
	ds_read_b128 v[48:51], v183
	s_waitcnt lgkmcnt(0)
	v_pk_fma_f32 v[48:49], v[72:73], v[48:49], v[76:77]
	s_nop 0
	v_pk_fma_f32 v[40:41], v[68:69], v[40:41], v[48:49]
	v_pk_fma_f32 v[50:51], v[74:75], v[50:51], v[78:79]
	v_pk_fma_f32 v[40:41], v[44:45], v[64:65], v[40:41]
	v_pk_fma_f32 v[42:43], v[70:71], v[42:43], v[50:51]
	v_pk_mul_f32 v[44:45], v[54:55], v[54:55]
	v_pk_fma_f32 v[44:45], v[44:45], v[254:255], v[252:253]
	v_pk_mul_f32 v[44:45], v[44:45], v[54:55]
	v_exp_f32_e32 v44, v44
	v_exp_f32_e32 v45, v45
	v_add_f32_e32 v44, 1.0, v44
	v_add_f32_e32 v45, 1.0, v45
	v_rcp_f32_e32 v44, v44
	v_rcp_f32_e32 v45, v45
	s_nop 0
	v_pk_fma_f32 v[42:43], v[46:47], v[66:67], v[42:43]
	v_pk_mul_f32 v[44:45], v[54:55], v[44:45]
	s_nop 0
	v_pk_mul_f32 v[40:41], v[40:41], v[44:45]
	s_nop 0
	v_cvt_pk_bf16_f32 v40, v40, v41
	s_nop 0
	s_nop 0
	v_pk_mul_f32 v[44:45], v[52:53], v[52:53]
	v_pk_fma_f32 v[44:45], v[44:45], v[254:255], v[252:253]
	v_pk_mul_f32 v[44:45], v[44:45], v[52:53]
	v_exp_f32_e32 v44, v44
	v_exp_f32_e32 v45, v45
	v_add_f32_e32 v44, 1.0, v44
	v_add_f32_e32 v45, 1.0, v45
	v_rcp_f32_e32 v44, v44
	v_rcp_f32_e32 v45, v45
	s_nop 0
	s_nop 0
	v_pk_mul_f32 v[44:45], v[52:53], v[44:45]
	s_nop 0
	v_pk_mul_f32 v[42:43], v[42:43], v[44:45]
	s_nop 0
	v_cvt_pk_bf16_f32 v41, v42, v43
	v_mov_b64_e32 v[42:43], s[10:11]
	v_mad_i64_i32 v[42:43], s[6:7], v114, s96, v[42:43]
	v_lshl_add_u64 v[42:43], v[174:175], 1, v[42:43]
	global_store_dwordx2 v[42:43], v[40:41], off offset:8
.LBB0_1322:
	s_or_b64 exec, exec, s[2:3]
	v_mov_b32_e32 v105, v104
	v_mov_b32_e32 v40, v104
	v_mov_b32_e32 v41, v104
	v_pk_mul_f32 v[38:39], v[38:39], v[40:41]
	v_pk_mul_f32 v[36:37], v[36:37], v[104:105]
	v_pk_mul_f32 v[34:35], v[34:35], v[40:41]
	v_pk_mul_f32 v[32:33], v[32:33], v[104:105]
	ds_write_b128 v168, v[36:39] offset:1024
	ds_write_b128 v168, v[32:35] offset:17408
	s_and_saveexec_b64 s[2:3], s[0:1]
	s_cbranch_execz .LBB0_1324
	ds_read_b128 v[40:43], v122 offset:16384
	ds_read_b128 v[44:47], v123 offset:16384
	s_waitcnt vmcnt(0) lgkmcnt(0)
	v_pk_fma_f32 v[46:47], v[90:91], v[46:47], v[94:95]
	v_pk_fma_f32 v[44:45], v[88:89], v[44:45], v[92:93]
	v_pk_fma_f32 v[42:43], v[82:83], v[42:43], v[46:47]
	v_pk_fma_f32 v[40:41], v[80:81], v[40:41], v[44:45]
	v_pk_fma_f32 v[44:45], v[34:35], v[86:87], v[42:43]
	v_pk_fma_f32 v[46:47], v[32:33], v[84:85], v[40:41]
	ds_read_b128 v[32:35], v122
	ds_read_b128 v[40:43], v123
	s_waitcnt lgkmcnt(0)
	v_pk_fma_f32 v[40:41], v[72:73], v[40:41], v[76:77]
	s_nop 0
	v_pk_fma_f32 v[32:33], v[68:69], v[32:33], v[40:41]
	v_pk_fma_f32 v[42:43], v[74:75], v[42:43], v[78:79]
	v_pk_fma_f32 v[32:33], v[36:37], v[64:65], v[32:33]
	v_pk_fma_f32 v[34:35], v[70:71], v[34:35], v[42:43]
	v_pk_mul_f32 v[36:37], v[46:47], v[46:47]
	v_pk_fma_f32 v[36:37], v[36:37], v[254:255], v[252:253]
	v_pk_mul_f32 v[36:37], v[36:37], v[46:47]
	v_exp_f32_e32 v36, v36
	v_exp_f32_e32 v37, v37
	v_add_f32_e32 v36, 1.0, v36
	v_add_f32_e32 v37, 1.0, v37
	v_rcp_f32_e32 v36, v36
	v_rcp_f32_e32 v37, v37
	s_nop 0
	v_pk_fma_f32 v[34:35], v[38:39], v[66:67], v[34:35]
	v_pk_mul_f32 v[36:37], v[46:47], v[36:37]
	s_nop 0
	v_pk_mul_f32 v[32:33], v[32:33], v[36:37]
	s_nop 0
	v_cvt_pk_bf16_f32 v32, v32, v33
	s_nop 0
	s_nop 0
	v_pk_mul_f32 v[36:37], v[44:45], v[44:45]
	v_pk_fma_f32 v[36:37], v[36:37], v[254:255], v[252:253]
	v_pk_mul_f32 v[36:37], v[36:37], v[44:45]
	v_exp_f32_e32 v36, v36
	v_exp_f32_e32 v37, v37
	v_add_f32_e32 v36, 1.0, v36
	v_add_f32_e32 v37, 1.0, v37
	v_rcp_f32_e32 v36, v36
	v_rcp_f32_e32 v37, v37
	s_nop 0
	s_nop 0
	v_pk_mul_f32 v[36:37], v[44:45], v[36:37]
	s_nop 0
	v_pk_mul_f32 v[34:35], v[34:35], v[36:37]
	s_nop 0
	v_cvt_pk_bf16_f32 v33, v34, v35
	v_mov_b64_e32 v[34:35], s[10:11]
	v_mad_i64_i32 v[34:35], s[6:7], v106, s96, v[34:35]
	v_lshl_add_u64 v[34:35], v[174:175], 1, v[34:35]
	global_store_dwordx2 v[34:35], v[32:33], off offset:8
.LBB0_1324:
	s_or_b64 exec, exec, s[2:3]
	v_mov_b32_e32 v97, v96
	v_mov_b32_e32 v32, v96
	v_mov_b32_e32 v33, v96
	v_pk_mul_f32 v[30:31], v[30:31], v[32:33]
	v_pk_mul_f32 v[28:29], v[28:29], v[96:97]
	v_pk_mul_f32 v[26:27], v[26:27], v[32:33]
	v_pk_mul_f32 v[24:25], v[24:25], v[96:97]
	ds_write_b128 v168, v[28:31]
	ds_write_b128 v168, v[24:27] offset:16384
	s_and_saveexec_b64 s[2:3], s[8:9]
	s_cbranch_execz .LBB0_1326
	ds_read_b128 v[32:35], v185 offset:16384
	ds_read_b128 v[36:39], v183 offset:16384
	s_waitcnt vmcnt(0) lgkmcnt(0)
	v_pk_fma_f32 v[38:39], v[90:91], v[38:39], v[94:95]
	v_pk_fma_f32 v[36:37], v[88:89], v[36:37], v[92:93]
	v_pk_fma_f32 v[34:35], v[82:83], v[34:35], v[38:39]
	v_pk_fma_f32 v[32:33], v[80:81], v[32:33], v[36:37]
	v_pk_fma_f32 v[36:37], v[26:27], v[86:87], v[34:35]
	v_pk_fma_f32 v[38:39], v[24:25], v[84:85], v[32:33]
	ds_read_b128 v[24:27], v185
	ds_read_b128 v[32:35], v183
	s_waitcnt lgkmcnt(0)
	v_pk_fma_f32 v[32:33], v[72:73], v[32:33], v[76:77]
	s_nop 0
	v_pk_fma_f32 v[24:25], v[68:69], v[24:25], v[32:33]
	v_pk_fma_f32 v[34:35], v[74:75], v[34:35], v[78:79]
	v_pk_fma_f32 v[24:25], v[28:29], v[64:65], v[24:25]
	v_pk_fma_f32 v[26:27], v[70:71], v[26:27], v[34:35]
	v_pk_mul_f32 v[28:29], v[38:39], v[38:39]
	v_pk_fma_f32 v[28:29], v[28:29], v[254:255], v[252:253]
	v_pk_mul_f32 v[28:29], v[28:29], v[38:39]
	v_exp_f32_e32 v28, v28
	v_exp_f32_e32 v29, v29
	v_add_f32_e32 v28, 1.0, v28
	v_add_f32_e32 v29, 1.0, v29
	v_rcp_f32_e32 v28, v28
	v_rcp_f32_e32 v29, v29
	s_nop 0
	v_pk_fma_f32 v[26:27], v[30:31], v[66:67], v[26:27]
	v_pk_mul_f32 v[28:29], v[38:39], v[28:29]
	s_nop 0
	v_pk_mul_f32 v[24:25], v[24:25], v[28:29]
	s_nop 0
	v_cvt_pk_bf16_f32 v24, v24, v25
	s_nop 0
	s_nop 0
	v_pk_mul_f32 v[28:29], v[36:37], v[36:37]
	v_pk_fma_f32 v[28:29], v[28:29], v[254:255], v[252:253]
	v_pk_mul_f32 v[28:29], v[28:29], v[36:37]
	v_exp_f32_e32 v28, v28
	v_exp_f32_e32 v29, v29
	v_add_f32_e32 v28, 1.0, v28
	v_add_f32_e32 v29, 1.0, v29
	v_rcp_f32_e32 v28, v28
	v_rcp_f32_e32 v29, v29
	s_nop 0
	s_nop 0
	v_pk_mul_f32 v[28:29], v[36:37], v[28:29]
	s_nop 0
	v_pk_mul_f32 v[26:27], v[26:27], v[28:29]
	s_nop 0
	v_cvt_pk_bf16_f32 v25, v26, v27
	v_mov_b64_e32 v[26:27], s[10:11]
	v_mad_i64_i32 v[26:27], s[6:7], v184, s96, v[26:27]
	v_lshl_add_u64 v[26:27], v[174:175], 1, v[26:27]
	global_store_dwordx2 v[26:27], v[24:25], off offset:8
.LBB0_1326:
	s_or_b64 exec, exec, s[2:3]
	v_mov_b32_e32 v99, v98
	v_mov_b32_e32 v24, v98
	v_mov_b32_e32 v25, v98
	v_pk_mul_f32 v[22:23], v[22:23], v[24:25]
	v_pk_mul_f32 v[20:21], v[20:21], v[98:99]
	v_pk_mul_f32 v[18:19], v[18:19], v[24:25]
	v_pk_mul_f32 v[16:17], v[16:17], v[98:99]
	ds_write_b128 v168, v[20:23] offset:1024
	ds_write_b128 v168, v[16:19] offset:17408
	s_and_saveexec_b64 s[2:3], s[0:1]
	s_cbranch_execz .LBB0_1328
	ds_read_b128 v[24:27], v122 offset:16384
	ds_read_b128 v[28:31], v123 offset:16384
	s_waitcnt vmcnt(0) lgkmcnt(0)
	v_pk_fma_f32 v[30:31], v[90:91], v[30:31], v[94:95]
	v_pk_fma_f32 v[28:29], v[88:89], v[28:29], v[92:93]
	v_pk_fma_f32 v[26:27], v[82:83], v[26:27], v[30:31]
	v_pk_fma_f32 v[24:25], v[80:81], v[24:25], v[28:29]
	v_pk_fma_f32 v[28:29], v[18:19], v[86:87], v[26:27]
	v_pk_fma_f32 v[30:31], v[16:17], v[84:85], v[24:25]
	ds_read_b128 v[16:19], v122
	ds_read_b128 v[24:27], v123
	s_waitcnt lgkmcnt(0)
	v_pk_fma_f32 v[24:25], v[72:73], v[24:25], v[76:77]
	s_nop 0
	v_pk_fma_f32 v[16:17], v[68:69], v[16:17], v[24:25]
	v_pk_fma_f32 v[26:27], v[74:75], v[26:27], v[78:79]
	v_pk_fma_f32 v[16:17], v[20:21], v[64:65], v[16:17]
	v_pk_fma_f32 v[18:19], v[70:71], v[18:19], v[26:27]
	v_pk_mul_f32 v[20:21], v[30:31], v[30:31]
	v_pk_fma_f32 v[20:21], v[20:21], v[254:255], v[252:253]
	v_pk_mul_f32 v[20:21], v[20:21], v[30:31]
	v_exp_f32_e32 v20, v20
	v_exp_f32_e32 v21, v21
	v_add_f32_e32 v20, 1.0, v20
	v_add_f32_e32 v21, 1.0, v21
	v_rcp_f32_e32 v20, v20
	v_rcp_f32_e32 v21, v21
	s_nop 0
	v_pk_fma_f32 v[18:19], v[22:23], v[66:67], v[18:19]
	v_pk_mul_f32 v[20:21], v[30:31], v[20:21]
	s_nop 0
	v_pk_mul_f32 v[16:17], v[16:17], v[20:21]
	s_nop 0
	v_cvt_pk_bf16_f32 v16, v16, v17
	s_nop 0
	s_nop 0
	v_pk_mul_f32 v[20:21], v[28:29], v[28:29]
	v_pk_fma_f32 v[20:21], v[20:21], v[254:255], v[252:253]
	v_pk_mul_f32 v[20:21], v[20:21], v[28:29]
	v_exp_f32_e32 v20, v20
	v_exp_f32_e32 v21, v21
	v_add_f32_e32 v20, 1.0, v20
	v_add_f32_e32 v21, 1.0, v21
	v_rcp_f32_e32 v20, v20
	v_rcp_f32_e32 v21, v21
	s_nop 0
	s_nop 0
	v_pk_mul_f32 v[20:21], v[28:29], v[20:21]
	s_nop 0
	v_pk_mul_f32 v[18:19], v[18:19], v[20:21]
	s_nop 0
	v_cvt_pk_bf16_f32 v17, v18, v19
	v_mov_b64_e32 v[18:19], s[10:11]
	v_mad_i64_i32 v[18:19], s[6:7], v101, s96, v[18:19]
	v_lshl_add_u64 v[18:19], v[174:175], 1, v[18:19]
	global_store_dwordx2 v[18:19], v[16:17], off offset:8
.LBB0_1328:
	s_or_b64 exec, exec, s[2:3]
	v_mov_b32_e32 v101, v100
	v_mov_b32_e32 v16, v100
	v_mov_b32_e32 v17, v100
	v_pk_mul_f32 v[14:15], v[14:15], v[16:17]
	v_pk_mul_f32 v[12:13], v[12:13], v[100:101]
	v_pk_mul_f32 v[10:11], v[10:11], v[16:17]
	v_pk_mul_f32 v[8:9], v[8:9], v[100:101]
	ds_write_b128 v168, v[12:15]
	ds_write_b128 v168, v[8:11] offset:16384
	s_and_saveexec_b64 s[2:3], s[0:1]
	s_cbranch_execz .LBB0_1330
	ds_read_b128 v[16:19], v185 offset:16384
	ds_read_b128 v[20:23], v183 offset:16384
	s_waitcnt vmcnt(0) lgkmcnt(0)
	v_pk_fma_f32 v[22:23], v[90:91], v[22:23], v[94:95]
	v_pk_fma_f32 v[20:21], v[88:89], v[20:21], v[92:93]
	v_pk_fma_f32 v[18:19], v[82:83], v[18:19], v[22:23]
	v_pk_fma_f32 v[16:17], v[80:81], v[16:17], v[20:21]
	v_pk_fma_f32 v[20:21], v[10:11], v[86:87], v[18:19]
	v_pk_fma_f32 v[22:23], v[8:9], v[84:85], v[16:17]
	ds_read_b128 v[8:11], v185
	ds_read_b128 v[16:19], v183
	s_waitcnt lgkmcnt(0)
	v_pk_fma_f32 v[16:17], v[72:73], v[16:17], v[76:77]
	s_nop 0
	v_pk_fma_f32 v[8:9], v[68:69], v[8:9], v[16:17]
	v_pk_fma_f32 v[18:19], v[74:75], v[18:19], v[78:79]
	v_pk_fma_f32 v[8:9], v[12:13], v[64:65], v[8:9]
	v_pk_fma_f32 v[10:11], v[70:71], v[10:11], v[18:19]
	v_pk_mul_f32 v[12:13], v[22:23], v[22:23]
	v_pk_fma_f32 v[12:13], v[12:13], v[254:255], v[252:253]
	v_pk_mul_f32 v[12:13], v[12:13], v[22:23]
	v_exp_f32_e32 v12, v12
	v_exp_f32_e32 v13, v13
	v_add_f32_e32 v12, 1.0, v12
	v_add_f32_e32 v13, 1.0, v13
	v_rcp_f32_e32 v12, v12
	v_rcp_f32_e32 v13, v13
	s_nop 0
	v_pk_fma_f32 v[10:11], v[14:15], v[66:67], v[10:11]
	v_pk_mul_f32 v[12:13], v[22:23], v[12:13]
	s_nop 0
	v_pk_mul_f32 v[8:9], v[8:9], v[12:13]
	s_nop 0
	v_cvt_pk_bf16_f32 v8, v8, v9
	s_nop 0
	s_nop 0
	v_pk_mul_f32 v[12:13], v[20:21], v[20:21]
	v_pk_fma_f32 v[12:13], v[12:13], v[254:255], v[252:253]
	v_pk_mul_f32 v[12:13], v[12:13], v[20:21]
	v_exp_f32_e32 v12, v12
	v_exp_f32_e32 v13, v13
	v_add_f32_e32 v12, 1.0, v12
	v_add_f32_e32 v13, 1.0, v13
	v_rcp_f32_e32 v12, v12
	v_rcp_f32_e32 v13, v13
	s_nop 0
	s_nop 0
	v_pk_mul_f32 v[12:13], v[20:21], v[12:13]
	s_nop 0
	v_pk_mul_f32 v[10:11], v[10:11], v[12:13]
	s_nop 0
	v_cvt_pk_bf16_f32 v9, v10, v11
	v_mov_b64_e32 v[10:11], s[10:11]
	v_mad_i64_i32 v[10:11], s[6:7], v103, s96, v[10:11]
	v_lshl_add_u64 v[10:11], v[174:175], 1, v[10:11]
	global_store_dwordx2 v[10:11], v[8:9], off offset:8
.LBB0_1330:
	s_or_b64 exec, exec, s[2:3]
	v_mov_b32_e32 v103, v102
	v_mov_b32_e32 v8, v102
	v_mov_b32_e32 v9, v102
	v_pk_mul_f32 v[6:7], v[6:7], v[8:9]
	v_pk_mul_f32 v[4:5], v[4:5], v[102:103]
	v_pk_mul_f32 v[2:3], v[2:3], v[8:9]
	v_pk_mul_f32 v[0:1], v[0:1], v[102:103]
	ds_write_b128 v168, v[4:7] offset:1024
	ds_write_b128 v168, v[0:3] offset:17408
	s_and_saveexec_b64 s[2:3], s[0:1]
	s_cbranch_execz .LBB0_1332
	ds_read_b128 v[8:11], v123 offset:16384
	ds_read_b128 v[12:15], v122 offset:16384
	ds_read_b128 v[16:19], v122
	ds_read_b128 v[20:23], v123
	s_waitcnt vmcnt(0) lgkmcnt(3)
	v_pk_fma_f32 v[10:11], v[90:91], v[10:11], v[94:95]
	v_pk_fma_f32 v[8:9], v[88:89], v[8:9], v[92:93]
	s_waitcnt lgkmcnt(2)
	v_pk_fma_f32 v[10:11], v[82:83], v[14:15], v[10:11]
	v_pk_fma_f32 v[8:9], v[80:81], v[12:13], v[8:9]
	v_pk_fma_f32 v[2:3], v[2:3], v[86:87], v[10:11]
	v_pk_fma_f32 v[0:1], v[0:1], v[84:85], v[8:9]
	s_waitcnt lgkmcnt(0)
	v_pk_fma_f32 v[8:9], v[74:75], v[22:23], v[78:79]
	v_pk_fma_f32 v[10:11], v[72:73], v[20:21], v[76:77]
	v_pk_fma_f32 v[8:9], v[70:71], v[18:19], v[8:9]
	v_pk_fma_f32 v[10:11], v[68:69], v[16:17], v[10:11]
	v_pk_fma_f32 v[6:7], v[6:7], v[66:67], v[8:9]
	v_pk_fma_f32 v[4:5], v[4:5], v[64:65], v[10:11]
	v_pk_mul_f32 v[8:9], v[0:1], v[0:1]
	v_pk_fma_f32 v[8:9], v[8:9], v[254:255], v[252:253]
	v_pk_mul_f32 v[8:9], v[8:9], v[0:1]
	v_exp_f32_e32 v8, v8
	v_exp_f32_e32 v9, v9
	v_add_f32_e32 v8, 1.0, v8
	v_add_f32_e32 v9, 1.0, v9
	v_rcp_f32_e32 v8, v8
	v_rcp_f32_e32 v9, v9
	s_nop 0
	v_pk_mul_f32 v[10:11], v[2:3], v[2:3]
	v_pk_fma_f32 v[10:11], v[10:11], v[254:255], v[252:253]
	v_pk_mul_f32 v[10:11], v[10:11], v[2:3]
	v_exp_f32_e32 v10, v10
	v_exp_f32_e32 v11, v11
	v_add_f32_e32 v10, 1.0, v10
	v_add_f32_e32 v11, 1.0, v11
	v_rcp_f32_e32 v10, v10
	v_rcp_f32_e32 v11, v11
	s_nop 0
	v_pk_mul_f32 v[0:1], v[0:1], v[8:9]
	s_nop 0
	v_pk_mul_f32 v[0:1], v[4:5], v[0:1]
	v_pk_mul_f32 v[2:3], v[2:3], v[10:11]
	v_cvt_pk_bf16_f32 v0, v0, v1
	v_pk_mul_f32 v[2:3], v[6:7], v[2:3]
	s_nop 0
	v_cvt_pk_bf16_f32 v1, v2, v3
	v_mov_b64_e32 v[2:3], s[10:11]
	v_mad_i64_i32 v[2:3], s[0:1], v107, s96, v[2:3]
	v_lshl_add_u64 v[2:3], v[174:175], 1, v[2:3]
	global_store_dwordx2 v[2:3], v[0:1], off offset:8
